# P4: all blocks run ym_finalize first (h still cache-resident), then the pool GEMM
# speedup vs baseline: 1.0059x; 1.0059x over previous
; #define OPAQUE_TID() int tid = threadIdx.x; asm volatile("" : "+v"(tid)); const int lane = tid & 63, wave = __builtin_amdgcn_readfirstlane(tid >> 6); (void)lane; (void)wave
; #define YM_LOAD(row) do { const bf16_t* ur_ = U + (size_t)(row) * LDU + cbase; _Pragma("unroll") for (int hp = 0; hp < 2; ++hp) { \
;         nh[hp] = *(const u32x4*)(ur_ + C_V + 512 * hp); nz[hp] = *(const u32x4*)(ur_ + C_ZM + 512 * hp); } } while (0)
; __device__ __forceinline__ void ym_finalize(const Args& a, bool dry = false) {
;     OPAQUE_TID();
;     bf16_t* U = (bf16_t*)(a.ws + WS_U);
;     const int gw = blockIdx.x * 8 + wave, NGW = gridDim.x * 8;
;     const int cbase = (lane >> 5) * 256 + 8 * (lane & 31);
;     f32x4 gh[2][2];
; #pragma unroll
;     for (int hp = 0; hp < 2; ++hp) { gh[hp][0] = *(const f32x4*)(a.in[16] + cbase + 512 * hp); gh[hp][1] = *(const f32x4*)(a.in[16] + cbase + 512 * hp + 4); }
;     u32x4 nh[2], nz[2];
;     ...
;     if (gw < MT) YM_LOAD(gw);
;     for (int row = gw; row < MT; row += NGW) {
;         u32x4 ch[2], cz[2];
; #pragma unroll
;         for (int hp = 0; hp < 2; ++hp) { ch[hp] = nh[hp]; cz[hp] = nz[hp]; }
;         if (row + NGW < MT) YM_LOAD(row + NGW);
; __global__ void __launch_bounds__(512, 2) fwd_megakernel(Args a) {
;     ...
;         if ((bid >> 3) & 1) ym_finalize(a);
.LBB0_1128:
	s_or_b64 exec, exec, s[0:1]
	s_bitcmp0_b32 s2, 3
	s_cselect_b64 s[4:5], -1, 0
	s_and_b64 vcc, exec, s[4:5]
	s_waitcnt lgkmcnt(0)
	s_barrier
	v_mov_b32_e32 v20, v180
	v_readlane_b32 s1, v254, 3
	v_readfirstlane_b32 s0, v20
	s_ashr_i32 s0, s0, 6
	s_add_i32 s10, s0, s1
	s_cmp_gt_i32 s10, 0x83ff
	s_cbranch_scc1 .LBB0_1134
	v_lshlrev_b32_e32 v0, 3, v20
	s_mul_i32 s0, s10, 0x3800
	v_and_b32_e32 v8, 0x1f8, v0
	s_mul_hi_i32 s1, s10, 0x3800
	s_add_u32 s0, s28, s0
	s_addc_u32 s1, s29, s1
	v_lshlrev_b32_e32 v48, 1, v8
	v_mov_b32_e32 v49, 0
	v_lshlrev_b32_e32 v21, 2, v8
	v_lshl_add_u64 v[8:9], s[0:1], 0, v[48:49]
	s_movk_i32 s6, 0x3000
	v_add_co_u32_e32 v22, vcc, s6, v8
	s_movk_i32 s11, 0x1000
	s_nop 0
	v_addc_co_u32_e32 v23, vcc, 0, v9, vcc
	v_add_co_u32_e32 v24, vcc, s11, v8
	global_load_dwordx4 v[0:3], v21, s[20:21] offset:2048
	global_load_dwordx4 v[4:7], v21, s[20:21] offset:2064
	v_addc_co_u32_e32 v25, vcc, 0, v9, vcc
	global_load_dwordx4 v[36:39], v[24:25], off
	global_load_dwordx4 v[16:19], v[24:25], off offset:1024
	global_load_dwordx4 v[44:47], v[22:23], off
	global_load_dwordx4 v[40:43], v[22:23], off offset:1024
	global_load_dwordx4 v[8:11], v21, s[20:21]
	global_load_dwordx4 v[12:15], v21, s[20:21] offset:16
	v_mbcnt_hi_u32_b32 v21, -1, v181
	v_and_b32_e32 v22, 64, v21
	v_xor_b32_e32 v23, 1, v21
	v_add_u32_e32 v22, 64, v22
	v_xor_b32_e32 v24, 2, v21
	v_cmp_lt_i32_e32 vcc, v23, v22
	v_xor_b32_e32 v25, 4, v21
	v_xor_b32_e32 v26, 8, v21
	v_cndmask_b32_e32 v23, v21, v23, vcc
	v_cmp_lt_i32_e32 vcc, v24, v22
	v_xor_b32_e32 v27, 16, v21
	s_add_i32 s6, s10, s34
	v_cndmask_b32_e32 v24, v21, v24, vcc
	v_cmp_lt_i32_e32 vcc, v25, v22
	v_and_b32_e32 v20, 63, v20
	s_mul_hi_i32 s7, s6, 0x3800
	v_cndmask_b32_e32 v25, v21, v25, vcc
	v_cmp_lt_i32_e32 vcc, v26, v22
	s_mulk_i32 s6, 0x3800
	v_lshlrev_b32_e32 v48, 4, v20
	v_cndmask_b32_e32 v26, v21, v26, vcc
	v_cmp_lt_i32_e32 vcc, v27, v22
	v_lshlrev_b32_e32 v51, 2, v23
	v_lshlrev_b32_e32 v52, 2, v24
	v_cndmask_b32_e32 v21, v21, v27, vcc
	v_lshlrev_b32_e32 v53, 2, v25
	v_lshlrev_b32_e32 v54, 2, v26
	v_lshlrev_b32_e32 v55, 2, v21
	s_add_u32 s6, s28, s6
	s_mul_hi_i32 s12, s34, 0x3800
	s_mul_i32 s13, s34, 0x3800
	v_mov_b32_e32 v50, 0x358637bd
	s_mov_b32 s14, 0x800000
	s_addc_u32 s7, s29, s7
	s_waitcnt vmcnt(5)
	v_mov_b64_e32 v[28:29], v[36:37]
	s_waitcnt vmcnt(4)
	v_mov_b64_e32 v[26:27], v[18:19]
	s_waitcnt vmcnt(3)
	v_mov_b64_e32 v[20:21], v[44:45]
	s_waitcnt vmcnt(2)
	v_mov_b64_e32 v[32:33], v[40:41]
	v_mov_b64_e32 v[24:25], v[16:17]
	v_mov_b64_e32 v[30:31], v[38:39]
	v_mov_b64_e32 v[22:23], v[46:47]
	v_mov_b64_e32 v[34:35], v[42:43]
	s_branch .LBB0_1132

; #define OPAQUE_TID() int tid = threadIdx.x; asm volatile("" : "+v"(tid)); const int lane = tid & 63, wave = __builtin_amdgcn_readfirstlane(tid >> 6); (void)lane; (void)wave
; #define YM_LOAD(row) do { const bf16_t* ur_ = U + (size_t)(row) * LDU + cbase; _Pragma("unroll") for (int hp = 0; hp < 2; ++hp) { \
;         nh[hp] = *(const u32x4*)(ur_ + C_V + 512 * hp); nz[hp] = *(const u32x4*)(ur_ + C_ZM + 512 * hp); } } while (0)
; __device__ __forceinline__ void ym_finalize(const Args& a, bool dry = false) {
;     OPAQUE_TID();
;     bf16_t* U = (bf16_t*)(a.ws + WS_U);
;     const int gw = blockIdx.x * 8 + wave, NGW = gridDim.x * 8;
;     const int cbase = (lane >> 5) * 256 + 8 * (lane & 31);
;     f32x4 gh[2][2];
; #pragma unroll
;     for (int hp = 0; hp < 2; ++hp) { gh[hp][0] = *(const f32x4*)(a.in[16] + cbase + 512 * hp); gh[hp][1] = *(const f32x4*)(a.in[16] + cbase + 512 * hp + 4); }
;     u32x4 nh[2], nz[2];
;     ...
;     if (gw < MT) YM_LOAD(gw);
;     for (int row = gw; row < MT; row += NGW) {
;         u32x4 ch[2], cz[2];
; #pragma unroll
;         for (int hp = 0; hp < 2; ++hp) { ch[hp] = nh[hp]; cz[hp] = nz[hp]; }
;         if (row + NGW < MT) YM_LOAD(row + NGW);
; __global__ void __launch_bounds__(512, 2) fwd_megakernel(Args a) {
;     ...
;         if (!((bid >> 3) & 1)) ym_finalize(a);
.LBB0_1148:
	s_andn2_b64 vcc, exec, s[4:5]
	s_branch .LBB0_1154
	v_mov_b32_e32 v20, v180
	v_readlane_b32 s1, v254, 3
	v_readfirstlane_b32 s0, v20
	s_ashr_i32 s0, s0, 6
	s_add_i32 s8, s0, s1
	s_cmp_gt_i32 s8, 0x83ff
	s_cbranch_scc1 .LBB0_1154
	v_lshlrev_b32_e32 v0, 3, v20
	s_mul_i32 s0, s8, 0x3800
	v_and_b32_e32 v8, 0x1f8, v0
	s_mul_hi_i32 s1, s8, 0x3800
	s_add_u32 s0, s28, s0
	s_addc_u32 s1, s29, s1
	v_lshlrev_b32_e32 v48, 1, v8
	v_mov_b32_e32 v49, 0
	v_lshlrev_b32_e32 v21, 2, v8
	v_lshl_add_u64 v[8:9], s[0:1], 0, v[48:49]
	s_movk_i32 s4, 0x3000
	v_add_co_u32_e32 v22, vcc, s4, v8
	s_movk_i32 s9, 0x1000
	s_nop 0
	v_addc_co_u32_e32 v23, vcc, 0, v9, vcc
	v_add_co_u32_e32 v24, vcc, s9, v8
	global_load_dwordx4 v[0:3], v21, s[20:21] offset:2048
	global_load_dwordx4 v[4:7], v21, s[20:21] offset:2064
	v_addc_co_u32_e32 v25, vcc, 0, v9, vcc
	global_load_dwordx4 v[36:39], v[24:25], off
	global_load_dwordx4 v[16:19], v[24:25], off offset:1024
	global_load_dwordx4 v[44:47], v[22:23], off
	global_load_dwordx4 v[40:43], v[22:23], off offset:1024
	global_load_dwordx4 v[8:11], v21, s[20:21]
	global_load_dwordx4 v[12:15], v21, s[20:21] offset:16
	v_mbcnt_hi_u32_b32 v21, -1, v181
	v_and_b32_e32 v22, 64, v21
	v_xor_b32_e32 v23, 1, v21
	v_add_u32_e32 v22, 64, v22
	v_xor_b32_e32 v24, 2, v21
	v_cmp_lt_i32_e32 vcc, v23, v22
	v_xor_b32_e32 v25, 4, v21
	v_xor_b32_e32 v26, 8, v21
	v_cndmask_b32_e32 v23, v21, v23, vcc
	v_cmp_lt_i32_e32 vcc, v24, v22
	v_xor_b32_e32 v27, 16, v21
	s_add_i32 s4, s8, s34
	v_cndmask_b32_e32 v24, v21, v24, vcc
	v_cmp_lt_i32_e32 vcc, v25, v22
	v_and_b32_e32 v20, 63, v20
	s_mul_hi_i32 s5, s4, 0x3800
	v_cndmask_b32_e32 v25, v21, v25, vcc
	v_cmp_lt_i32_e32 vcc, v26, v22
	s_mulk_i32 s4, 0x3800
	v_lshlrev_b32_e32 v48, 4, v20
	v_cndmask_b32_e32 v26, v21, v26, vcc
	v_cmp_lt_i32_e32 vcc, v27, v22
	v_lshlrev_b32_e32 v51, 2, v23
	v_lshlrev_b32_e32 v52, 2, v24
	v_cndmask_b32_e32 v21, v21, v27, vcc
	v_lshlrev_b32_e32 v53, 2, v25
	v_lshlrev_b32_e32 v54, 2, v26
	v_lshlrev_b32_e32 v55, 2, v21
	s_add_u32 s4, s28, s4
	s_mul_hi_i32 s10, s34, 0x3800
	s_mul_i32 s11, s34, 0x3800
	v_mov_b32_e32 v50, 0x358637bd
	s_mov_b32 s12, 0x800000
	s_addc_u32 s5, s29, s5
	s_waitcnt vmcnt(5)
	v_mov_b64_e32 v[28:29], v[36:37]
	s_waitcnt vmcnt(4)
	v_mov_b64_e32 v[26:27], v[18:19]
	s_waitcnt vmcnt(3)
	v_mov_b64_e32 v[20:21], v[44:45]
	s_waitcnt vmcnt(2)
	v_mov_b64_e32 v[32:33], v[40:41]
	v_mov_b64_e32 v[24:25], v[16:17]
	v_mov_b64_e32 v[30:31], v[38:39]
	v_mov_b64_e32 v[22:23], v[46:47]
	v_mov_b64_e32 v[34:35], v[42:43]
	s_branch .LBB0_1152
